# prep step 3: the qk waves take the mirrored tile row so every SIMD holds five tiles
# baseline (speedup 1.0000x reference)
.LBB0_218:
	s_or_b64 exec, exec, s[0:1]
	s_waitcnt lgkmcnt(0)
	s_barrier
	v_add_u32_e32 v13, s88, v234
	v_add_u32_e32 v13, 0x21600, v13
	v_add_u32_e32 v11, v234, v233
	v_add_u32_e32 v14, v234, v232
	ds_read_b128 v[16:19], v13 offset:256
	ds_read_b128 v[20:23], v13 offset:272
	ds_read_b128 v[24:27], v13 offset:512
	ds_read_b128 v[28:31], v13 offset:528
	ds_read_b128 v[32:35], v13 offset:0
	ds_read_b128 v[36:39], v13 offset:16
	ds_read_b64 v[40:41], v11 offset:0
	ds_read_b64 v[42:43], v11 offset:528
	ds_read_b64 v[44:45], v11 offset:1056
	ds_read_b64 v[46:47], v11 offset:1584
	ds_read_b64 v[48:49], v11 offset:2112
	ds_read_b64 v[50:51], v11 offset:2640
	ds_read_b64 v[52:53], v11 offset:3168
	ds_read_b64 v[54:55], v11 offset:3696
	ds_read_b64 v[56:57], v11 offset:33792
	ds_read_b64 v[58:59], v11 offset:34320
	ds_read_b64 v[60:61], v11 offset:34848
	ds_read_b64 v[62:63], v11 offset:35376
	ds_read_b64 v[64:65], v11 offset:35904
	ds_read_b64 v[66:67], v11 offset:36432
	ds_read_b64 v[68:69], v11 offset:36960
	ds_read_b64 v[70:71], v11 offset:37488
	v_add_u32_e32 v9, 0x18c00, v14
	v_add_u32_e32 v10, 0x1d000, v14
	s_mov_b32 s29, 0x15c00000
	v_add_co_u32_e32 v4, vcc, s29, v122
	s_nop 1
	v_addc_co_u32_e32 v5, vcc, 0, v123, vcc
	s_waitcnt lgkmcnt(15)
	v_add_f32_e32 v16, 0x358637bd, v16
	v_add_f32_e32 v17, 0x358637bd, v17
	v_add_f32_e32 v18, 0x358637bd, v18
	v_add_f32_e32 v19, 0x358637bd, v19
	v_add_f32_e32 v20, 0x358637bd, v20
	v_add_f32_e32 v21, 0x358637bd, v21
	v_add_f32_e32 v22, 0x358637bd, v22
	v_add_f32_e32 v23, 0x358637bd, v23
	v_add_f32_e32 v24, 0x358637bd, v24
	v_add_f32_e32 v25, 0x358637bd, v25
	v_add_f32_e32 v26, 0x358637bd, v26
	v_add_f32_e32 v27, 0x358637bd, v27
	v_add_f32_e32 v28, 0x358637bd, v28
	v_add_f32_e32 v29, 0x358637bd, v29
	v_add_f32_e32 v30, 0x358637bd, v30
	v_add_f32_e32 v31, 0x358637bd, v31
	v_rsq_f32_e32 v16, v16
	v_rsq_f32_e32 v17, v17
	v_rsq_f32_e32 v18, v18
	v_rsq_f32_e32 v19, v19
	v_rsq_f32_e32 v20, v20
	v_rsq_f32_e32 v21, v21
	v_rsq_f32_e32 v22, v22
	v_rsq_f32_e32 v23, v23
	v_rsq_f32_e32 v24, v24
	v_rsq_f32_e32 v25, v25
	v_rsq_f32_e32 v26, v26
	v_rsq_f32_e32 v27, v27
	v_rsq_f32_e32 v28, v28
	v_rsq_f32_e32 v29, v29
	v_rsq_f32_e32 v30, v30
	v_rsq_f32_e32 v31, v31
	v_mul_f32_e32 v16, 0x3db504f3, v16
	v_mul_f32_e32 v17, 0x3db504f3, v17
	v_mul_f32_e32 v18, 0x3db504f3, v18
	v_mul_f32_e32 v19, 0x3db504f3, v19
	v_mul_f32_e32 v20, 0x3db504f3, v20
	v_mul_f32_e32 v21, 0x3db504f3, v21
	v_mul_f32_e32 v22, 0x3db504f3, v22
	v_mul_f32_e32 v23, 0x3db504f3, v23
	s_waitcnt lgkmcnt(7)
	v_mul_f32_e32 v40, v40, v16
	v_mul_f32_e32 v41, v41, v16
	v_mul_f32_e32 v56, v56, v24
	v_mul_f32_e32 v57, v57, v24
	v_cvt_pk_bf16_f32 v6, v40, v41
	v_cvt_pk_bf16_f32 v7, v56, v57
	v_mul_f32_e32 v40, v40, v32
	v_mul_f32_e32 v41, v41, v32
	ds_write_b32 v9, v6 offset:0
	ds_write_b32 v10, v7 offset:0
	ds_write_b64 v11, v[56:57] offset:33792
	v_cvt_pk_bf16_f32 v8, v40, v41
	global_store_dword v[4:5], v8, off offset:0
	s_waitcnt lgkmcnt(9)
	v_mul_f32_e32 v42, v42, v17
	v_mul_f32_e32 v43, v43, v17
	v_mul_f32_e32 v58, v58, v25
	v_mul_f32_e32 v59, v59, v25
	v_cvt_pk_bf16_f32 v6, v42, v43
	v_cvt_pk_bf16_f32 v7, v58, v59
	v_mul_f32_e32 v42, v42, v33
	v_mul_f32_e32 v43, v43, v33
	ds_write_b32 v9, v6 offset:272
	ds_write_b32 v10, v7 offset:272
	ds_write_b64 v11, v[58:59] offset:34320
	v_cvt_pk_bf16_f32 v8, v42, v43
	global_store_dword v[4:5], v8, off offset:256
	s_waitcnt lgkmcnt(11)
	v_mul_f32_e32 v44, v44, v18
	v_mul_f32_e32 v45, v45, v18
	v_mul_f32_e32 v60, v60, v26
	v_mul_f32_e32 v61, v61, v26
	v_cvt_pk_bf16_f32 v6, v44, v45
	v_cvt_pk_bf16_f32 v7, v60, v61
	v_mul_f32_e32 v44, v44, v34
	v_mul_f32_e32 v45, v45, v34
	ds_write_b32 v9, v6 offset:544
	ds_write_b32 v10, v7 offset:544
	ds_write_b64 v11, v[60:61] offset:34848
	v_cvt_pk_bf16_f32 v8, v44, v45
	global_store_dword v[4:5], v8, off offset:512
	s_waitcnt lgkmcnt(13)
	v_mul_f32_e32 v46, v46, v19
	v_mul_f32_e32 v47, v47, v19
	v_mul_f32_e32 v62, v62, v27
	v_mul_f32_e32 v63, v63, v27
	v_cvt_pk_bf16_f32 v6, v46, v47
	v_cvt_pk_bf16_f32 v7, v62, v63
	v_mul_f32_e32 v46, v46, v35
	v_mul_f32_e32 v47, v47, v35
	ds_write_b32 v9, v6 offset:816
	ds_write_b32 v10, v7 offset:816
	ds_write_b64 v11, v[62:63] offset:35376
	v_cvt_pk_bf16_f32 v8, v46, v47
	global_store_dword v[4:5], v8, off offset:768
	s_waitcnt lgkmcnt(15)
	v_mul_f32_e32 v48, v48, v20
	v_mul_f32_e32 v49, v49, v20
	v_mul_f32_e32 v64, v64, v28
	v_mul_f32_e32 v65, v65, v28
	v_cvt_pk_bf16_f32 v6, v48, v49
	v_cvt_pk_bf16_f32 v7, v64, v65
	v_mul_f32_e32 v48, v48, v36
	v_mul_f32_e32 v49, v49, v36
	ds_write_b32 v9, v6 offset:1088
	ds_write_b32 v10, v7 offset:1088
	ds_write_b64 v11, v[64:65] offset:35904
	v_cvt_pk_bf16_f32 v8, v48, v49
	global_store_dword v[4:5], v8, off offset:1024
	s_waitcnt lgkmcnt(15)
	v_mul_f32_e32 v50, v50, v21
	v_mul_f32_e32 v51, v51, v21
	v_mul_f32_e32 v66, v66, v29
	v_mul_f32_e32 v67, v67, v29
	v_cvt_pk_bf16_f32 v6, v50, v51
	v_cvt_pk_bf16_f32 v7, v66, v67
	v_mul_f32_e32 v50, v50, v37
	v_mul_f32_e32 v51, v51, v37
	ds_write_b32 v9, v6 offset:1360
	ds_write_b32 v10, v7 offset:1360
	ds_write_b64 v11, v[66:67] offset:36432
	v_cvt_pk_bf16_f32 v8, v50, v51
	global_store_dword v[4:5], v8, off offset:1280
	v_mul_f32_e32 v52, v52, v22
	v_mul_f32_e32 v53, v53, v22
	v_mul_f32_e32 v68, v68, v30
	v_mul_f32_e32 v69, v69, v30
	v_cvt_pk_bf16_f32 v6, v52, v53
	v_cvt_pk_bf16_f32 v7, v68, v69
	v_mul_f32_e32 v52, v52, v38
	v_mul_f32_e32 v53, v53, v38
	ds_write_b32 v9, v6 offset:1632
	ds_write_b32 v10, v7 offset:1632
	ds_write_b64 v11, v[68:69] offset:36960
	v_cvt_pk_bf16_f32 v8, v52, v53
	global_store_dword v[4:5], v8, off offset:1536
	v_mul_f32_e32 v54, v54, v23
	v_mul_f32_e32 v55, v55, v23
	v_mul_f32_e32 v70, v70, v31
	v_mul_f32_e32 v71, v71, v31
	v_cvt_pk_bf16_f32 v6, v54, v55
	v_cvt_pk_bf16_f32 v7, v70, v71
	v_mul_f32_e32 v54, v54, v39
	v_mul_f32_e32 v55, v55, v39
	ds_write_b32 v9, v6 offset:1904
	ds_write_b32 v10, v7 offset:1904
	ds_write_b64 v11, v[70:71] offset:37488
	v_cvt_pk_bf16_f32 v8, v54, v55
	global_store_dword v[4:5], v8, off offset:1792
	s_add_i32 s28, s88, 32
	s_mov_b32 s1, 0
	s_movk_i32 s0, 0x800
	s_cmpk_eq_i32 s0, 0x800
	v_add_u32_e32 v28, 0x18c00, v234
	s_waitcnt lgkmcnt(0)
	s_barrier
	s_ashr_i32 s65, s64, 31
	s_lshr_b32 s28, s88, 5
	s_and_b32 s28, s28, 3
	s_cmp_lt_u32 s88, 0x80
	s_cbranch_scc1 .Lp3_noflip
	s_sub_u32 s28, 3, s28
.Lp3_noflip:
	v_and_b32_e32 v154, 15, v160
	v_lshrrev_b32_e32 v155, 4, v160
	v_mul_u32_u24_e32 v156, 0x110, v154
	v_lshl_add_u32 v156, v155, 4, v156
	v_add_u32_e32 v167, 0x1d000, v234
	v_add_u32_e32 v167, v167, v156
	s_mul_i32 s29, s28, 0x1100
	v_add_u32_e32 v157, s29, v167
	s_lshl_b32 s29, s28, 6
	v_lshl_add_u32 v169, v155, 4, v234
	v_add_u32_e32 v169, 0x21400, v169
	v_add_u32_e32 v169, s29, v169
	v_lshl_add_u32 v170, v154, 2, v234
	v_add_u32_e32 v170, 0x21500, v170
	v_lshlrev_b32_e32 v156, 2, v155
	v_sub_u32_e32 v172, v154, v156
	v_subrev_u32_e32 v173, 1, v172
	v_subrev_u32_e32 v174, 2, v172
	v_subrev_u32_e32 v175, 3, v172
	s_cmp_lt_u32 s88, 0x80
	s_cbranch_scc0 .Lp3_w1
	v_mul_u32_u24_e32 v171, 0x440, v155
	v_lshl_add_u32 v171, v154, 2, v171
	s_mul_i32 s29, s28, 0x1100
	v_add3_u32 v171, v171, v234, s29
	ds_read_b128 v[4:7], v157 offset:0
	ds_read_b128 v[8:11], v157 offset:64
	ds_read_b128 v[12:15], v157 offset:128
	ds_read_b128 v[16:19], v157 offset:192
	ds_read_b128 v[24:27], v169 offset:256
	ds_read_b128 v[244:247], v169
	ds_read_b32 v146, v170 offset:0
	ds_read_b32 v147, v170 offset:64
	ds_read_b32 v148, v170 offset:128
	ds_read_b32 v149, v170 offset:192
	ds_read_b128 v[32:35], v167 offset:0
	ds_read_b128 v[36:39], v167 offset:64
	ds_read_b128 v[40:43], v167 offset:128
	ds_read_b128 v[44:47], v167 offset:192
	s_cmp_lt_u32 s28, 1
	s_cbranch_scc1 .Lp3_w0_a
	ds_read_b128 v[48:51], v167 offset:4352
	ds_read_b128 v[52:55], v167 offset:4416
	ds_read_b128 v[56:59], v167 offset:4480
	ds_read_b128 v[60:63], v167 offset:4544
